# grid barrier: the arrival that completes the early-finishing workgroup class on an XCD starts one extra L2 write-back (8 of the 12 seams)
# baseline (speedup 1.0000x reference)
; __device__ __forceinline__ unsigned xb_add(unsigned* p, unsigned v) { return __hip_atomic_fetch_add(p, v, __ATOMIC_RELAXED, __HIP_MEMORY_SCOPE_AGENT); }
; __device__ __forceinline__ void xcd_barrier(const XcdBarrier& b) {
;     ...
;         const unsigned old = xb_add(&bar[XB_XSUB(b.x)], 1u);
;         const unsigned gen = old / nloc;
;         if (old + 1u == (gen + 1u) * nloc) {
;             __builtin_amdgcn_fence(__ATOMIC_RELEASE, "agent");
;             asm volatile("s_waitcnt vmcnt(0)" ::: "memory");
;             const unsigned og = xb_add(&bar[XB_TOP], 1u);
;             const unsigned tg = og / nx;
;             if (og + 1u == (tg + 1u) * nx) xb_add(&bar[XB_TOPGEN], 1u);
.LBB0_197:
	s_or_b64 exec, exec, s[28:29]
	v_cvt_f32_u32_e32 v4, v2
	s_waitcnt vmcnt(0)
	v_readfirstlane_b32 s6, v3
	v_sub_u32_e32 v3, 0, v2
	v_rcp_iflag_f32_e32 v4, v4
	v_add_u32_e32 v5, s6, v1
	v_mul_u32_u24_e32 v250, 1, v2
	v_mul_u32_u24_e32 v251, 11, v2
	v_lshrrev_b32_e32 v251, 5, v251
	v_add3_u32 v250, v250, v251, -1
	v_cmp_ne_u32_e64 s[28:29], v250, v5
	s_nop 3
	s_and_b64 s[28:29], s[28:29], exec
	s_cbranch_scc1 .Lka_skip_1
	buffer_wbl2 sc1
.Lka_skip_1:
	v_mul_f32_e32 v4, 0x4f7ffffe, v4
	v_cvt_u32_f32_e32 v4, v4
	v_mul_lo_u32 v1, v3, v4
	v_mul_hi_u32 v1, v4, v1
	v_add_u32_e32 v1, v4, v1
	v_mul_hi_u32 v1, v5, v1
	v_mul_lo_u32 v3, v1, v2
	v_sub_u32_e32 v3, v5, v3
	v_add_u32_e32 v4, 1, v1
	v_cmp_ge_u32_e32 vcc, v3, v2
	s_nop 1
	v_cndmask_b32_e32 v1, v1, v4, vcc
	v_sub_u32_e32 v4, v3, v2
	v_cndmask_b32_e32 v3, v3, v4, vcc
	v_add_u32_e32 v4, 1, v1
	v_cmp_ge_u32_e32 vcc, v3, v2
	v_add_u32_e32 v3, 1, v5
	s_nop 0
	v_cndmask_b32_e32 v1, v1, v4, vcc
	v_mul_lo_u32 v4, v2, v1
	v_add_u32_e32 v2, v4, v2
	v_cmp_ne_u32_e32 vcc, v3, v2
	s_and_saveexec_b64 s[6:7], vcc
	s_xor_b64 s[6:7], exec, s[6:7]
	s_cbranch_execz .LBB0_211
	s_waitcnt lgkmcnt(0)
	buffer_inv sc1
	v_mov_b32_e32 v0, 0x83500
	global_load_dword v0, v0, s[72:73] sc1
	s_add_u32 s62, s72, 0x83500
	s_addc_u32 s63, s73, 0
	s_waitcnt vmcnt(0)
	v_cmp_eq_u32_e32 vcc, v0, v1
	s_and_saveexec_b64 s[46:47], vcc
	s_cbranch_execz .LBB0_210
	s_add_u32 s50, s72, 0x80200
	s_addc_u32 s51, s73, 0
	s_mov_b32 s8, 1
	s_mov_b64 s[64:65], 0
	v_mov_b32_e32 v0, 0
	s_branch .LBB0_201

; __device__ __forceinline__ unsigned xb_add(unsigned* p, unsigned v) { return __hip_atomic_fetch_add(p, v, __ATOMIC_RELAXED, __HIP_MEMORY_SCOPE_AGENT); }
; __device__ __forceinline__ void xcd_barrier(const XcdBarrier& b) {
;     ...
;         const unsigned old = xb_add(&bar[XB_XSUB(b.x)], 1u);
;         const unsigned gen = old / nloc;
;         if (old + 1u == (gen + 1u) * nloc) {
;             __builtin_amdgcn_fence(__ATOMIC_RELEASE, "agent");
;             asm volatile("s_waitcnt vmcnt(0)" ::: "memory");
;             const unsigned og = xb_add(&bar[XB_TOP], 1u);
;             const unsigned tg = og / nx;
;             if (og + 1u == (tg + 1u) * nx) xb_add(&bar[XB_TOPGEN], 1u);
.LBB0_332:
	s_or_b64 exec, exec, s[28:29]
	v_cvt_f32_u32_e32 v4, v2
	s_waitcnt vmcnt(0)
	v_readfirstlane_b32 s6, v3
	v_sub_u32_e32 v3, 0, v2
	v_rcp_iflag_f32_e32 v4, v4
	v_add_u32_e32 v5, s6, v1
	v_mul_u32_u24_e32 v250, 2, v2
	v_mul_u32_u24_e32 v251, 16, v2
	v_lshrrev_b32_e32 v251, 5, v251
	v_add3_u32 v250, v250, v251, -1
	v_cmp_ne_u32_e64 s[28:29], v250, v5
	s_nop 3
	s_and_b64 s[28:29], s[28:29], exec
	s_cbranch_scc1 .Lka_skip_2
	buffer_wbl2 sc1
.Lka_skip_2:
	v_mul_f32_e32 v4, 0x4f7ffffe, v4
	v_cvt_u32_f32_e32 v4, v4
	v_mul_lo_u32 v1, v3, v4
	v_mul_hi_u32 v1, v4, v1
	v_add_u32_e32 v1, v4, v1
	v_mul_hi_u32 v1, v5, v1
	v_mul_lo_u32 v3, v1, v2
	v_sub_u32_e32 v3, v5, v3
	v_add_u32_e32 v4, 1, v1
	v_cmp_ge_u32_e32 vcc, v3, v2
	s_nop 1
	v_cndmask_b32_e32 v1, v1, v4, vcc
	v_sub_u32_e32 v4, v3, v2
	v_cndmask_b32_e32 v3, v3, v4, vcc
	v_add_u32_e32 v4, 1, v1
	v_cmp_ge_u32_e32 vcc, v3, v2
	v_add_u32_e32 v3, 1, v5
	s_nop 0
	v_cndmask_b32_e32 v1, v1, v4, vcc
	v_mul_lo_u32 v4, v2, v1
	v_add_u32_e32 v2, v4, v2
	v_cmp_ne_u32_e32 vcc, v3, v2
	s_and_saveexec_b64 s[6:7], vcc
	s_xor_b64 s[6:7], exec, s[6:7]
	s_cbranch_execz .LBB0_346
	s_waitcnt lgkmcnt(0)
	buffer_inv sc1
	v_mov_b32_e32 v0, 0x83500
	global_load_dword v0, v0, s[72:73] sc1
	s_add_u32 s50, s72, 0x83500
	s_addc_u32 s51, s73, 0
	s_waitcnt vmcnt(0)
	v_cmp_eq_u32_e32 vcc, v0, v1
	s_and_saveexec_b64 s[42:43], vcc
	s_cbranch_execz .LBB0_345
	s_add_u32 s46, s72, 0x80200
	s_addc_u32 s47, s73, 0
	s_mov_b32 s8, 1
	s_mov_b64 s[52:53], 0
	v_mov_b32_e32 v0, 0
	s_branch .LBB0_336

; __device__ __forceinline__ unsigned xb_add(unsigned* p, unsigned v) { return __hip_atomic_fetch_add(p, v, __ATOMIC_RELAXED, __HIP_MEMORY_SCOPE_AGENT); }
; __device__ __forceinline__ void xcd_barrier(const XcdBarrier& b) {
;     ...
;         const unsigned old = xb_add(&bar[XB_XSUB(b.x)], 1u);
;         const unsigned gen = old / nloc;
;         if (old + 1u == (gen + 1u) * nloc) {
;             __builtin_amdgcn_fence(__ATOMIC_RELEASE, "agent");
;             asm volatile("s_waitcnt vmcnt(0)" ::: "memory");
;             const unsigned og = xb_add(&bar[XB_TOP], 1u);
;             const unsigned tg = og / nx;
;             if (og + 1u == (tg + 1u) * nx) xb_add(&bar[XB_TOPGEN], 1u);
.LBB0_429:
	s_or_b64 exec, exec, s[6:7]
	v_cvt_f32_u32_e32 v4, v2
	s_waitcnt vmcnt(0)
	v_readfirstlane_b32 s4, v3
	v_sub_u32_e32 v3, 0, v2
	v_rcp_iflag_f32_e32 v4, v4
	v_add_u32_e32 v5, s4, v1
	v_mul_u32_u24_e32 v250, 3, v2
	v_mul_u32_u24_e32 v251, 24, v2
	v_lshrrev_b32_e32 v251, 5, v251
	v_add3_u32 v250, v250, v251, -1
	v_cmp_ne_u32_e64 s[6:7], v250, v5
	s_nop 3
	s_and_b64 s[6:7], s[6:7], exec
	s_cbranch_scc1 .Lka_skip_3
	buffer_wbl2 sc1
.Lka_skip_3:
	v_mul_f32_e32 v4, 0x4f7ffffe, v4
	v_cvt_u32_f32_e32 v4, v4
	v_mul_lo_u32 v1, v3, v4
	v_mul_hi_u32 v1, v4, v1
	v_add_u32_e32 v1, v4, v1
	v_mul_hi_u32 v1, v5, v1
	v_mul_lo_u32 v3, v1, v2
	v_sub_u32_e32 v3, v5, v3
	v_add_u32_e32 v4, 1, v1
	v_cmp_ge_u32_e32 vcc, v3, v2
	s_nop 1
	v_cndmask_b32_e32 v1, v1, v4, vcc
	v_sub_u32_e32 v4, v3, v2
	v_cndmask_b32_e32 v3, v3, v4, vcc
	v_add_u32_e32 v4, 1, v1
	v_cmp_ge_u32_e32 vcc, v3, v2
	v_add_u32_e32 v3, 1, v5
	s_nop 0
	v_cndmask_b32_e32 v1, v1, v4, vcc
	v_mul_lo_u32 v4, v2, v1
	v_add_u32_e32 v2, v4, v2
	v_cmp_ne_u32_e32 vcc, v3, v2
	s_and_saveexec_b64 s[4:5], vcc
	s_xor_b64 s[4:5], exec, s[4:5]
	s_cbranch_execz .LBB0_443
	s_waitcnt lgkmcnt(0)
	buffer_inv sc1
	v_mov_b32_e32 v0, 0x83500
	global_load_dword v0, v0, s[72:73] sc1
	s_add_u32 s46, s72, 0x83500
	s_addc_u32 s47, s73, 0
	s_waitcnt vmcnt(0)
	v_cmp_eq_u32_e32 vcc, v0, v1
	s_and_saveexec_b64 s[6:7], vcc
	s_cbranch_execz .LBB0_442
	s_add_u32 s40, s72, 0x80200
	s_addc_u32 s41, s73, 0
	s_mov_b32 s8, 1
	s_mov_b64 s[50:51], 0
	v_mov_b32_e32 v0, 0
	s_branch .LBB0_433

; __device__ __forceinline__ unsigned xb_add(unsigned* p, unsigned v) { return __hip_atomic_fetch_add(p, v, __ATOMIC_RELAXED, __HIP_MEMORY_SCOPE_AGENT); }
; __device__ __forceinline__ void xcd_barrier(const XcdBarrier& b) {
;     ...
;         const unsigned old = xb_add(&bar[XB_XSUB(b.x)], 1u);
;         const unsigned gen = old / nloc;
;         if (old + 1u == (gen + 1u) * nloc) {
;             __builtin_amdgcn_fence(__ATOMIC_RELEASE, "agent");
;             asm volatile("s_waitcnt vmcnt(0)" ::: "memory");
;             const unsigned og = xb_add(&bar[XB_TOP], 1u);
;             const unsigned tg = og / nx;
;             if (og + 1u == (tg + 1u) * nx) xb_add(&bar[XB_TOPGEN], 1u);
.LBB0_540:
	s_or_b64 exec, exec, s[12:13]
	v_cvt_f32_u32_e32 v4, v2
	s_waitcnt vmcnt(0)
	v_readfirstlane_b32 s6, v3
	v_sub_u32_e32 v3, 0, v2
	v_rcp_iflag_f32_e32 v4, v4
	v_add_u32_e32 v5, s6, v1
	v_mul_u32_u24_e32 v250, 4, v2
	v_mul_u32_u24_e32 v251, 24, v2
	v_lshrrev_b32_e32 v251, 5, v251
	v_add3_u32 v250, v250, v251, -1
	v_cmp_ne_u32_e64 s[12:13], v250, v5
	s_nop 3
	s_and_b64 s[12:13], s[12:13], exec
	s_cbranch_scc1 .Lka_skip_4
	buffer_wbl2 sc1
.Lka_skip_4:
	v_mul_f32_e32 v4, 0x4f7ffffe, v4
	v_cvt_u32_f32_e32 v4, v4
	v_mul_lo_u32 v1, v3, v4
	v_mul_hi_u32 v1, v4, v1
	v_add_u32_e32 v1, v4, v1
	v_mul_hi_u32 v1, v5, v1
	v_mul_lo_u32 v3, v1, v2
	v_sub_u32_e32 v3, v5, v3
	v_add_u32_e32 v4, 1, v1
	v_cmp_ge_u32_e32 vcc, v3, v2
	s_nop 1
	v_cndmask_b32_e32 v1, v1, v4, vcc
	v_sub_u32_e32 v4, v3, v2
	v_cndmask_b32_e32 v3, v3, v4, vcc
	v_add_u32_e32 v4, 1, v1
	v_cmp_ge_u32_e32 vcc, v3, v2
	v_add_u32_e32 v3, 1, v5
	s_nop 0
	v_cndmask_b32_e32 v1, v1, v4, vcc
	v_mul_lo_u32 v4, v2, v1
	v_add_u32_e32 v2, v4, v2
	v_cmp_ne_u32_e32 vcc, v3, v2
	s_and_saveexec_b64 s[6:7], vcc
	s_xor_b64 s[6:7], exec, s[6:7]
	s_cbranch_execz .LBB0_554
	s_waitcnt lgkmcnt(0)
	buffer_inv sc1
	v_mov_b32_e32 v0, 0x83500
	global_load_dword v0, v0, s[72:73] sc1
	s_add_u32 s38, s72, 0x83500
	s_addc_u32 s39, s73, 0
	s_waitcnt vmcnt(0)
	v_cmp_eq_u32_e32 vcc, v0, v1
	s_and_saveexec_b64 s[12:13], vcc
	s_cbranch_execz .LBB0_553
	s_add_u32 s22, s72, 0x80200
	s_addc_u32 s23, s73, 0
	s_mov_b32 s8, 1
	s_mov_b64 s[42:43], 0
	v_mov_b32_e32 v0, 0
	s_branch .LBB0_544

; __device__ __forceinline__ unsigned xb_add(unsigned* p, unsigned v) { return __hip_atomic_fetch_add(p, v, __ATOMIC_RELAXED, __HIP_MEMORY_SCOPE_AGENT); }
; __device__ __forceinline__ void xcd_barrier(const XcdBarrier& b) {
;     ...
;         const unsigned old = xb_add(&bar[XB_XSUB(b.x)], 1u);
;         const unsigned gen = old / nloc;
;         if (old + 1u == (gen + 1u) * nloc) {
;             __builtin_amdgcn_fence(__ATOMIC_RELEASE, "agent");
;             asm volatile("s_waitcnt vmcnt(0)" ::: "memory");
;             const unsigned og = xb_add(&bar[XB_TOP], 1u);
;             const unsigned tg = og / nx;
;             if (og + 1u == (tg + 1u) * nx) xb_add(&bar[XB_TOPGEN], 1u);
.LBB0_637:
	s_or_b64 exec, exec, s[12:13]
	v_cvt_f32_u32_e32 v4, v2
	s_waitcnt vmcnt(0)
	v_readfirstlane_b32 s6, v3
	v_sub_u32_e32 v3, 0, v2
	v_rcp_iflag_f32_e32 v4, v4
	v_add_u32_e32 v5, s6, v1
	v_mul_u32_u24_e32 v250, 5, v2
	v_mul_u32_u24_e32 v251, 16, v2
	v_lshrrev_b32_e32 v251, 5, v251
	v_add3_u32 v250, v250, v251, -1
	v_cmp_ne_u32_e64 s[12:13], v250, v5
	s_nop 3
	s_and_b64 s[12:13], s[12:13], exec
	s_cbranch_scc1 .Lka_skip_5
	buffer_wbl2 sc1
.Lka_skip_5:
	v_mul_f32_e32 v4, 0x4f7ffffe, v4
	v_cvt_u32_f32_e32 v4, v4
	v_mul_lo_u32 v1, v3, v4
	v_mul_hi_u32 v1, v4, v1
	v_add_u32_e32 v1, v4, v1
	v_mul_hi_u32 v1, v5, v1
	v_mul_lo_u32 v3, v1, v2
	v_sub_u32_e32 v3, v5, v3
	v_add_u32_e32 v4, 1, v1
	v_cmp_ge_u32_e32 vcc, v3, v2
	s_nop 1
	v_cndmask_b32_e32 v1, v1, v4, vcc
	v_sub_u32_e32 v4, v3, v2
	v_cndmask_b32_e32 v3, v3, v4, vcc
	v_add_u32_e32 v4, 1, v1
	v_cmp_ge_u32_e32 vcc, v3, v2
	v_add_u32_e32 v3, 1, v5
	s_nop 0
	v_cndmask_b32_e32 v1, v1, v4, vcc
	v_mul_lo_u32 v4, v2, v1
	v_add_u32_e32 v2, v4, v2
	v_cmp_ne_u32_e32 vcc, v3, v2
	s_and_saveexec_b64 s[6:7], vcc
	s_xor_b64 s[6:7], exec, s[6:7]
	s_cbranch_execz .LBB0_651
	s_waitcnt lgkmcnt(0)
	buffer_inv sc1
	v_mov_b32_e32 v0, 0x83500
	global_load_dword v0, v0, s[72:73] sc1
	s_add_u32 s40, s72, 0x83500
	s_addc_u32 s41, s73, 0
	s_waitcnt vmcnt(0)
	v_cmp_eq_u32_e32 vcc, v0, v1
	s_and_saveexec_b64 s[12:13], vcc
	s_cbranch_execz .LBB0_650
	s_add_u32 s22, s72, 0x80200
	s_addc_u32 s23, s73, 0
	s_mov_b32 s8, 1
	s_mov_b64 s[42:43], 0
	v_mov_b32_e32 v0, 0
	s_branch .LBB0_641

; __device__ __forceinline__ unsigned xb_add(unsigned* p, unsigned v) { return __hip_atomic_fetch_add(p, v, __ATOMIC_RELAXED, __HIP_MEMORY_SCOPE_AGENT); }
; __device__ __forceinline__ void xcd_barrier(const XcdBarrier& b) {
;     ...
;         const unsigned old = xb_add(&bar[XB_XSUB(b.x)], 1u);
;         const unsigned gen = old / nloc;
;         if (old + 1u == (gen + 1u) * nloc) {
;             __builtin_amdgcn_fence(__ATOMIC_RELEASE, "agent");
;             asm volatile("s_waitcnt vmcnt(0)" ::: "memory");
;             const unsigned og = xb_add(&bar[XB_TOP], 1u);
;             const unsigned tg = og / nx;
;             if (og + 1u == (tg + 1u) * nx) xb_add(&bar[XB_TOPGEN], 1u);
.LBB0_811:
	s_or_b64 exec, exec, s[24:25]
	v_cvt_f32_u32_e32 v4, v2
	s_waitcnt vmcnt(0)
	v_readfirstlane_b32 s6, v3
	v_sub_u32_e32 v3, 0, v2
	v_rcp_iflag_f32_e32 v4, v4
	v_add_u32_e32 v5, s6, v1
	v_mul_u32_u24_e32 v250, 7, v2
	v_mul_u32_u24_e32 v251, 13, v2
	v_lshrrev_b32_e32 v251, 5, v251
	v_add3_u32 v250, v250, v251, -1
	v_cmp_ne_u32_e64 s[24:25], v250, v5
	s_nop 3
	s_and_b64 s[24:25], s[24:25], exec
	s_cbranch_scc1 .Lka_skip_7
	buffer_wbl2 sc1
.Lka_skip_7:
	v_mul_f32_e32 v4, 0x4f7ffffe, v4
	v_cvt_u32_f32_e32 v4, v4
	v_mul_lo_u32 v1, v3, v4
	v_mul_hi_u32 v1, v4, v1
	v_add_u32_e32 v1, v4, v1
	v_mul_hi_u32 v1, v5, v1
	v_mul_lo_u32 v3, v1, v2
	v_sub_u32_e32 v3, v5, v3
	v_add_u32_e32 v4, 1, v1
	v_cmp_ge_u32_e32 vcc, v3, v2
	s_nop 1
	v_cndmask_b32_e32 v1, v1, v4, vcc
	v_sub_u32_e32 v4, v3, v2
	v_cndmask_b32_e32 v3, v3, v4, vcc
	v_add_u32_e32 v4, 1, v1
	v_cmp_ge_u32_e32 vcc, v3, v2
	v_add_u32_e32 v3, 1, v5
	s_nop 0
	v_cndmask_b32_e32 v1, v1, v4, vcc
	v_mul_lo_u32 v4, v2, v1
	v_add_u32_e32 v2, v4, v2
	v_cmp_ne_u32_e32 vcc, v3, v2
	s_and_saveexec_b64 s[6:7], vcc
	s_xor_b64 s[6:7], exec, s[6:7]
	s_cbranch_execz .LBB0_825
	s_waitcnt lgkmcnt(0)
	buffer_inv sc1
	v_mov_b32_e32 v0, 0x83500
	global_load_dword v0, v0, s[72:73] sc1
	s_add_u32 s38, s72, 0x83500
	s_addc_u32 s39, s73, 0
	s_waitcnt vmcnt(0)
	v_cmp_eq_u32_e32 vcc, v0, v1
	s_and_saveexec_b64 s[24:25], vcc
	s_cbranch_execz .LBB0_824
	s_add_u32 s26, s72, 0x80200
	s_addc_u32 s27, s73, 0
	s_mov_b32 s8, 1
	s_mov_b64 s[40:41], 0
	v_mov_b32_e32 v0, 0
	s_branch .LBB0_815

; __device__ __forceinline__ unsigned xb_add(unsigned* p, unsigned v) { return __hip_atomic_fetch_add(p, v, __ATOMIC_RELAXED, __HIP_MEMORY_SCOPE_AGENT); }
; __device__ __forceinline__ void xcd_barrier(const XcdBarrier& b) {
;     ...
;         const unsigned old = xb_add(&bar[XB_XSUB(b.x)], 1u);
;         const unsigned gen = old / nloc;
;         if (old + 1u == (gen + 1u) * nloc) {
;             __builtin_amdgcn_fence(__ATOMIC_RELEASE, "agent");
;             asm volatile("s_waitcnt vmcnt(0)" ::: "memory");
;             const unsigned og = xb_add(&bar[XB_TOP], 1u);
;             const unsigned tg = og / nx;
;             if (og + 1u == (tg + 1u) * nx) xb_add(&bar[XB_TOPGEN], 1u);
.LBB0_1126:
	s_or_b64 exec, exec, s[14:15]
	v_cvt_f32_u32_e32 v4, v2
	s_waitcnt vmcnt(0)
	v_readfirstlane_b32 s6, v3
	v_sub_u32_e32 v3, 0, v2
	v_rcp_iflag_f32_e32 v4, v4
	v_add_u32_e32 v5, s6, v1
	v_mul_u32_u24_e32 v250, 9, v2
	v_mul_u32_u24_e32 v251, 24, v2
	v_lshrrev_b32_e32 v251, 5, v251
	v_add3_u32 v250, v250, v251, -1
	v_cmp_ne_u32_e64 s[14:15], v250, v5
	s_nop 3
	s_and_b64 s[14:15], s[14:15], exec
	s_cbranch_scc1 .Lka_skip_9
	buffer_wbl2 sc1
.Lka_skip_9:
	v_mul_f32_e32 v4, 0x4f7ffffe, v4
	v_cvt_u32_f32_e32 v4, v4
	v_mul_lo_u32 v1, v3, v4
	v_mul_hi_u32 v1, v4, v1
	v_add_u32_e32 v1, v4, v1
	v_mul_hi_u32 v1, v5, v1
	v_mul_lo_u32 v3, v1, v2
	v_sub_u32_e32 v3, v5, v3
	v_add_u32_e32 v4, 1, v1
	v_cmp_ge_u32_e32 vcc, v3, v2
	s_nop 1
	v_cndmask_b32_e32 v1, v1, v4, vcc
	v_sub_u32_e32 v4, v3, v2
	v_cndmask_b32_e32 v3, v3, v4, vcc
	v_add_u32_e32 v4, 1, v1
	v_cmp_ge_u32_e32 vcc, v3, v2
	v_add_u32_e32 v3, 1, v5
	s_nop 0
	v_cndmask_b32_e32 v1, v1, v4, vcc
	v_mul_lo_u32 v4, v2, v1
	v_add_u32_e32 v2, v4, v2
	v_cmp_ne_u32_e32 vcc, v3, v2
	s_and_saveexec_b64 s[6:7], vcc
	s_xor_b64 s[6:7], exec, s[6:7]
	s_cbranch_execz .LBB0_1140
	s_waitcnt lgkmcnt(0)
	buffer_inv sc1
	v_mov_b32_e32 v0, 0x83500
	global_load_dword v0, v0, s[72:73] sc1
	s_add_u32 s18, s72, 0x83500
	s_addc_u32 s19, s73, 0
	s_waitcnt vmcnt(0)
	v_cmp_eq_u32_e32 vcc, v0, v1
	s_and_saveexec_b64 s[14:15], vcc
	s_cbranch_execz .LBB0_1139
	s_add_u32 s16, s72, 0x80200
	s_addc_u32 s17, s73, 0
	s_mov_b32 s8, 1
	s_mov_b64 s[20:21], 0
	v_mov_b32_e32 v0, 0
	s_branch .LBB0_1130

; __device__ __forceinline__ unsigned xb_add(unsigned* p, unsigned v) { return __hip_atomic_fetch_add(p, v, __ATOMIC_RELAXED, __HIP_MEMORY_SCOPE_AGENT); }
; __device__ __forceinline__ void xcd_barrier(const XcdBarrier& b) {
;     ...
;         const unsigned old = xb_add(&bar[XB_XSUB(b.x)], 1u);
;         const unsigned gen = old / nloc;
;         if (old + 1u == (gen + 1u) * nloc) {
;             __builtin_amdgcn_fence(__ATOMIC_RELEASE, "agent");
;             asm volatile("s_waitcnt vmcnt(0)" ::: "memory");
;             const unsigned og = xb_add(&bar[XB_TOP], 1u);
;             const unsigned tg = og / nx;
;             if (og + 1u == (tg + 1u) * nx) xb_add(&bar[XB_TOPGEN], 1u);
.LBB0_1349:
	s_or_b64 exec, exec, s[12:13]
	v_cvt_f32_u32_e32 v4, v2
	s_waitcnt vmcnt(0)
	v_readfirstlane_b32 s6, v3
	v_sub_u32_e32 v3, 0, v2
	v_rcp_iflag_f32_e32 v4, v4
	v_add_u32_e32 v5, s6, v1
	v_mul_u32_u24_e32 v250, 11, v2
	v_mul_u32_u24_e32 v251, 16, v2
	v_lshrrev_b32_e32 v251, 5, v251
	v_add3_u32 v250, v250, v251, -1
	v_cmp_ne_u32_e64 s[12:13], v250, v5
	s_nop 3
	s_and_b64 s[12:13], s[12:13], exec
	s_cbranch_scc1 .Lka_skip_11
	buffer_wbl2 sc1
.Lka_skip_11:
	v_mul_f32_e32 v4, 0x4f7ffffe, v4
	v_cvt_u32_f32_e32 v4, v4
	v_mul_lo_u32 v1, v3, v4
	v_mul_hi_u32 v1, v4, v1
	v_add_u32_e32 v1, v4, v1
	v_mul_hi_u32 v1, v5, v1
	v_mul_lo_u32 v3, v1, v2
	v_sub_u32_e32 v3, v5, v3
	v_add_u32_e32 v4, 1, v1
	v_cmp_ge_u32_e32 vcc, v3, v2
	s_nop 1
	v_cndmask_b32_e32 v1, v1, v4, vcc
	v_sub_u32_e32 v4, v3, v2
	v_cndmask_b32_e32 v3, v3, v4, vcc
	v_add_u32_e32 v4, 1, v1
	v_cmp_ge_u32_e32 vcc, v3, v2
	v_add_u32_e32 v3, 1, v5
	s_nop 0
	v_cndmask_b32_e32 v1, v1, v4, vcc
	v_mul_lo_u32 v4, v2, v1
	v_add_u32_e32 v2, v4, v2
	v_cmp_ne_u32_e32 vcc, v3, v2
	s_and_saveexec_b64 s[6:7], vcc
	s_xor_b64 s[6:7], exec, s[6:7]
	s_cbranch_execz .LBB0_1363
	s_waitcnt lgkmcnt(0)
	buffer_inv sc1
	v_mov_b32_e32 v0, 0x83500
	global_load_dword v0, v0, s[72:73] sc1
	s_add_u32 s16, s72, 0x83500
	s_addc_u32 s17, s73, 0
	s_waitcnt vmcnt(0)
	v_cmp_eq_u32_e32 vcc, v0, v1
	s_and_saveexec_b64 s[12:13], vcc
	s_cbranch_execz .LBB0_1362
	s_add_u32 s14, s72, 0x80200
	s_addc_u32 s15, s73, 0
	s_mov_b32 s8, 1
	s_mov_b64 s[18:19], 0
	v_mov_b32_e32 v0, 0
	s_branch .LBB0_1353
